# v33 + grid-barrier spin loops poll without s_sleep (tight poll)
# speedup vs baseline: 1.0037x; 1.0037x over previous
; __global__ void __launch_bounds__(256, 2) mega(Params p, int ph_lo, int ph_hi) {
;     ...
;             if (ph_hi < 0) cg::this_grid().sync();
;             xcd_barrier(xb);
.LBB0_894:
	global_load_dword v2, v1, s[8:9] offset:32 sc1
	s_waitcnt vmcnt(0)
	v_and_b32_e32 v2, 0xffff0000, v2
	v_cmp_ne_u32_e32 vcc, v2, v0
	s_or_b64 s[10:11], vcc, s[10:11]
	s_andn2_b64 exec, exec, s[10:11]
	s_cbranch_execnz .LBB0_894

; DEVI unsigned xb_ld(unsigned* p) { return __hip_atomic_load(p, __ATOMIC_RELAXED, __HIP_MEMORY_SCOPE_AGENT); }
; DEVI void xcd_barrier_complete(unsigned* bar, unsigned x, unsigned& nloc, unsigned& nx) {
;     ...
;     for (;;) {
;         sum = 0u; cnt = 0u; mine = 0u;
; #pragma unroll
;         for (unsigned j = 0; j < 16; ++j) { const unsigned c = xb_ld(&bar[XB_XCNT(j)]); sum += c; cnt += (c > 0u) ? 1u : 0u; mine = (j == x) ? c : mine; }
;         if (sum == G) break;
;         __builtin_amdgcn_s_sleep(1);
;         if ((++sp & 255u) == 0u) { if (xb_ld(&bar[XB_TMO])) break; if (sp > XB_SPIN_CAP) { atomicAdd(&bar[XB_TMO], 1u); break; } }
;     }
.LBB0_901:
	v_readlane_b32 s8, v222, 32
	v_readlane_b32 s9, v222, 33
	s_mov_b64 s[10:11], -1
	s_nop 3
	global_load_dword v0, v1, s[8:9] sc1
	v_readlane_b32 s8, v222, 34
	v_readlane_b32 s9, v222, 35
	s_nop 4
	global_load_dword v2, v1, s[8:9] sc1
	v_readlane_b32 s8, v222, 36
	v_readlane_b32 s9, v222, 37
	s_waitcnt vmcnt(0)
	v_add_u32_e32 v17, v2, v0
	s_nop 2
	global_load_dword v3, v1, s[8:9] sc1
	v_readlane_b32 s8, v222, 38
	v_readlane_b32 s9, v222, 39
	s_waitcnt vmcnt(0)
	v_add_u32_e32 v17, v17, v3
	s_nop 2
	global_load_dword v4, v1, s[8:9] sc1
	v_readlane_b32 s8, v222, 40
	v_readlane_b32 s9, v222, 41
	s_waitcnt vmcnt(0)
	v_add_u32_e32 v17, v17, v4
	s_nop 2
	global_load_dword v5, v1, s[8:9] sc1
	v_readlane_b32 s8, v222, 42
	v_readlane_b32 s9, v222, 43
	s_waitcnt vmcnt(0)
	v_add_u32_e32 v17, v17, v5
	s_nop 2
	global_load_dword v6, v1, s[8:9] sc1
	v_readlane_b32 s8, v222, 44
	v_readlane_b32 s9, v222, 45
	s_waitcnt vmcnt(0)
	v_add_u32_e32 v17, v17, v6
	s_nop 2
	global_load_dword v7, v1, s[8:9] sc1
	v_readlane_b32 s8, v222, 46
	v_readlane_b32 s9, v222, 47
	s_waitcnt vmcnt(0)
	v_add_u32_e32 v17, v17, v7
	s_nop 2
	global_load_dword v8, v1, s[8:9] sc1
	v_readlane_b32 s8, v222, 48
	v_readlane_b32 s9, v222, 49
	s_waitcnt vmcnt(0)
	v_add_u32_e32 v17, v17, v8
	s_nop 2
	global_load_dword v9, v1, s[8:9] sc1
	v_readlane_b32 s8, v222, 50
	v_readlane_b32 s9, v222, 51
	s_waitcnt vmcnt(0)
	v_add_u32_e32 v17, v17, v9
	s_nop 2
	global_load_dword v10, v1, s[8:9] sc1
	v_readlane_b32 s8, v222, 52
	v_readlane_b32 s9, v222, 53
	s_waitcnt vmcnt(0)
	v_add_u32_e32 v17, v17, v10
	s_nop 2
	global_load_dword v11, v1, s[8:9] sc1
	v_readlane_b32 s8, v222, 54
	v_readlane_b32 s9, v222, 55
	s_waitcnt vmcnt(0)
	v_add_u32_e32 v17, v17, v11
	s_nop 2
	global_load_dword v12, v1, s[8:9] sc1
	v_readlane_b32 s8, v222, 56
	v_readlane_b32 s9, v222, 57
	s_waitcnt vmcnt(0)
	v_add_u32_e32 v17, v17, v12
	s_nop 2
	global_load_dword v13, v1, s[8:9] sc1
	v_readlane_b32 s8, v222, 58
	v_readlane_b32 s9, v222, 59
	s_waitcnt vmcnt(0)
	v_add_u32_e32 v17, v17, v13
	s_nop 2
	global_load_dword v14, v1, s[8:9] sc1
	v_readlane_b32 s8, v222, 60
	v_readlane_b32 s9, v222, 61
	s_waitcnt vmcnt(0)
	v_add_u32_e32 v17, v17, v14
	s_nop 2
	global_load_dword v15, v1, s[8:9] sc1
	v_readlane_b32 s8, v222, 62
	v_readlane_b32 s9, v222, 63
	s_waitcnt vmcnt(0)
	v_add_u32_e32 v17, v17, v15
	s_nop 2
	global_load_dword v16, v1, s[8:9] sc1
	s_mov_b64 s[8:9], -1
	s_waitcnt vmcnt(0)
	v_add_u32_e32 v17, v17, v16
	v_cmp_eq_u32_e32 vcc, s4, v17
	s_cbranch_vccnz .LBB0_900
	s_and_b32 s8, s6, 0xff
	s_cmp_eq_u32 s8, 0
	s_mov_b64 s[8:9], -1
	s_mov_b64 s[14:15], -1
	s_cbranch_scc1 .LBB0_905
	s_and_b64 vcc, exec, s[14:15]
	s_cbranch_vccz .LBB0_900

.LBB0_919:
	s_and_b32 s6, s4, 0xff
	s_mov_b64 s[26:27], -1
	s_cmp_lg_u32 s6, 0
	s_mov_b64 s[34:35], -1
	s_cbranch_scc0 .LBB0_922
	s_and_b64 vcc, exec, s[34:35]
	s_cbranch_vccz .LBB0_918
